# phase0b moved into P1 last-round shadow; P3 split into 256 prompt-tile units + grid barrier + 16 sample-tile units run by WGs 0-15 concurrently with P4 (piecewise P4 unit schedule, release/acquire fla
# speedup vs baseline: 1.0648x; 1.0150x over previous
.LBB0_305:
	s_mov_b32 s99, 1
	s_branch .LBB0_1525

.LBB0_1456:
	s_or_b64 exec, exec, s[6:7]
	s_movk_i32 s98, 0x100
	s_movk_i32 s97, 32
.Lp3_entry:
	s_mov_b64 s[8:9], s[0:1]
	v_mov_b32_e32 v1, v174
	s_cmp_lt_i32 s2, s98
	s_waitcnt lgkmcnt(0)
	s_barrier
	s_cselect_b64 s[10:11], -1, 0
	s_cmp_ge_i32 s2, s98
	v_readfirstlane_b32 s14, v1
	s_cbranch_scc1 .LBB0_1458
	s_ashr_i32 s3, s2, 31
	s_lshr_b32 s3, s3, 29
	s_add_i32 s3, s2, s3
	s_ashr_i32 s4, s3, 3
	s_and_b32 s3, s3, -8
	s_sub_i32 s3, s2, s3
	s_cmp_lt_i32 s3, 0
	s_mov_b32 s5, s97
	s_mul_i32 s3, s3, s5
	s_add_i32 s3, s3, s4
	s_ashr_i32 s4, s3, 31
	s_lshr_b32 s4, s4, 27
	s_add_i32 s4, s3, s4
	s_ashr_i32 s4, s4, 5
	s_lshl_b32 s6, s4, 3
	s_sub_i32 s5, 0x44, s6
	s_lshl_b32 s4, s4, 5
	s_min_u32 s7, s5, 8
	s_sub_i32 s3, s3, s4
	s_sext_i32_i8 s4, s3
	v_cvt_f32_ubyte0_e32 v2, s7
	v_cvt_f32_i32_e32 v0, s4
	v_rcp_iflag_f32_e32 v3, v2
	s_ashr_i32 s4, s4, 30
	s_or_b32 s12, s4, 1
	v_mul_f32_e32 v3, v0, v3
	v_trunc_f32_e32 v3, v3
	v_fma_f32 v0, -v3, v2, v0
	v_cvt_i32_f32_e32 v3, v3
	v_cmp_ge_f32_e64 s[4:5], |v0|, v2
	s_and_b64 s[4:5], s[4:5], exec
	s_cselect_b32 s4, s12, 0
	v_readfirstlane_b32 s5, v3
	s_add_i32 s4, s5, s4
	s_sext_i32_i8 s48, s4
	s_mul_i32 s4, s4, s7
	s_sub_i32 s3, s3, s4
	s_sext_i32_i8 s3, s3
	s_add_i32 s50, s6, s3

.LBB0_1461:
	s_add_u32 s28, s22, 0x90000
	s_addc_u32 s29, s23, 0
	s_add_u32 s30, s22, 0x2800000
	s_addc_u32 s31, s23, 0
	s_add_u32 s34, s22, 0x6c00000
	s_addc_u32 s35, s23, 0
	s_lshl_b32 s9, s9, 5
	s_mov_b64 s[36:37], 0x80
	s_and_b32 s16, s9, 0x60
	s_add_i32 m0, s49, 0x18000
	v_lshl_add_u64 v[8:9], v[8:9], 0, s[36:37]
	s_lshl_b32 s15, s8, 13
	s_lshl_b32 s9, s16, 7
	s_waitcnt vmcnt(2)
	s_barrier
	global_load_lds_dwordx4 v[8:9], off
	v_lshl_add_u64 v[6:7], v[6:7], 0, s[36:37]
	s_add_i32 m0, s49, 0x1a000
	s_add_i32 s59, s49, 0x8000
	s_add_i32 s60, s49, 0xa000
	global_load_lds_dwordx4 v[6:7], off
	v_lshl_add_u64 v[2:3], v[2:3], 0, s[36:37]
	s_mov_b32 m0, s59
	s_add_u32 s10, s12, 0x80080
	global_load_lds_dwordx4 v[2:3], off
	v_lshl_add_u64 v[2:3], v[4:5], 0, s[36:37]
	s_mov_b32 m0, s60
	s_addc_u32 s11, s13, 0
	global_load_lds_dwordx4 v[2:3], off
	s_add_i32 m0, s49, 0x1c000
	v_lshl_add_u64 v[2:3], s[10:11], 0, v[146:147]
	global_load_lds_dwordx4 v[2:3], off
	v_lshl_add_u64 v[2:3], s[10:11], 0, v[150:151]
	s_add_i32 m0, s49, 0x1e000
	s_mov_b64 s[10:11], 0x80080
	global_load_lds_dwordx4 v[2:3], off
	v_bfe_u32 v3, v1, 4, 2
	v_and_b32_e32 v2, 15, v1
	v_lshlrev_b32_e32 v4, 4, v3
	v_lshlrev_b32_e32 v1, 2, v1
	v_lshl_or_b32 v176, s8, 6, v2
	v_lshl_or_b32 v2, v2, 6, v4
	v_and_b32_e32 v1, 32, v1
	v_bitop3_b32 v4, v2, s15, v1 bitop3:0xde
	v_bitop3_b32 v177, v2, s9, v1 bitop3:0xde
	v_lshlrev_b32_e32 v1, 15, v10
	v_and_b32_e32 v1, 0xffff0000, v1
	v_lshl_add_u32 v1, v11, 12, v1
	v_and_b32_e32 v2, 1, v10
	v_lshl_or_b32 v1, v2, 6, v1
	v_lshl_add_u32 v2, v12, 1, v1
	v_lshlrev_b32_e32 v1, 15, v13
	v_cmp_eq_u32_e64 s[8:9], 0, v3
	v_lshl_or_b32 v179, v3, 3, s16
	v_mov_b32_e32 v3, v0
	v_and_b32_e32 v1, 0xffff0000, v1
	v_lshl_add_u64 v[152:153], v[2:3], 0, s[10:11]
	v_lshl_add_u32 v1, v14, 12, v1
	v_and_b32_e32 v2, 1, v13
	s_waitcnt vmcnt(6)
	s_cmpk_lt_u32 s14, 0x100
	v_lshl_or_b32 v1, v2, 6, v1
	s_cselect_b64 s[38:39], -1, 0
	v_lshl_add_u32 v2, v15, 1, v1
	s_add_i32 s65, 0, 0x10000
	s_add_i32 s68, 0, 0x14000
	v_lshlrev_b32_e32 v178, 1, v176
	s_ashr_i32 s61, s70, 31
	s_mov_b32 s62, s70
	s_ashr_i32 s63, s2, 31
	v_lshl_add_u64 v[154:155], v[2:3], 0, s[10:11]
	v_mov_b32_e32 v156, s98
	v_mov_b32_e32 v157, 0
	v_add_u32_e32 v158, -1, v156
	v_mov_b32_e32 v159, 0
	v_add_u32_e32 v180, s65, v177
	v_add_u32_e32 v181, s68, v177
	v_add_u32_e32 v182, 0, v4
	v_mov_b32_e32 v183, 0x358637bd
	s_mov_b32 s69, 0x800000
	s_movk_i32 s72, 0x3fff
	s_movk_i32 s73, 0x3f7f
	s_movk_i32 s74, 0x3f6f
	s_movk_i32 s75, 0x3f5f
	s_movk_i32 s76, 0x3f4f
	v_mbcnt_hi_u32_b32 v184, -1, v175
	s_barrier
	s_branch .LBB0_1464

.LBB0_1525:
	s_cmp_eq_u32 s99, 3
	s_cbranch_scc0 .Lp3_notpass2
	s_mov_b32 s2, s96
.Lp3_notpass2:
	s_abs_i32 s3, s70
	v_cvt_f32_u32_e32 v0, s3
	s_sub_i32 s4, 0, s3
	s_mov_b64 s[18:19], s[0:1]
	v_rcp_iflag_f32_e32 v0, v0
	s_nop 0
	v_mul_f32_e32 v0, 0x4f7ffffe, v0
	v_cvt_u32_f32_e32 v1, v0
	v_mov_b32_e32 v0, v174
	v_readfirstlane_b32 s5, v1
	s_mul_i32 s4, s4, s5
	s_mul_hi_u32 s4, s5, s4
	s_add_i32 s5, s5, s4
	s_mul_hi_u32 s4, s5, 0x110
	s_mul_i32 s4, s4, s3
	s_sub_i32 s4, 0x110, s4
	s_sub_i32 s5, s4, s3
	s_cmp_ge_u32 s4, s3
	s_cselect_b32 s4, s5, s4
	s_sub_i32 s5, s4, s3
	s_cmp_ge_u32 s4, s3
	s_cselect_b32 s3, s5, s4
	s_cmp_gt_i32 s70, 63
	s_cselect_b64 s[4:5], -1, 0
	s_cmp_lg_u32 s3, 0
	s_cselect_b64 s[8:9], -1, 0
	s_sub_i32 s10, s70, 32
	s_and_b64 s[4:5], s[4:5], s[8:9]
	s_cmp_lt_i32 s3, s10
	s_cselect_b64 s[8:9], -1, 0
	s_and_b64 s[4:5], s[4:5], s[8:9]
	s_and_b64 s[4:5], s[4:5], exec
	s_cselect_b32 s3, s3, 0
	s_cmp_eq_u32 s99, 1
	s_cselect_b32 s3, 0x60, s3
	s_cmp_ge_i32 s2, s3
	s_cselect_b64 s[16:17], -1, 0
	s_cmp_eq_u32 s99, 2
	s_cbranch_scc1 .LBB0_1768
	s_cmp_eq_u32 s99, 3
	s_cbranch_scc1 .Lp3_pass2_done
	s_cmp_lt_i32 s2, s3
	s_cbranch_scc1 .LBB0_1768
	s_waitcnt lgkmcnt(0)
	v_ashrrev_i32_e32 v2, 6, v0
	s_sub_i32 s4, s2, s3
	v_lshl_add_u32 v18, s4, 3, v2
	s_sub_i32 s4, s70, s3
	s_load_dwordx2 s[20:21], s[18:19], 0x128
	v_lshlrev_b32_e32 v15, 14, v2
	s_lshl_b32 s4, s4, 3
	v_ashrrev_i32_e32 v2, 31, v18
	v_and_b32_e32 v2, s4, v2
	v_and_b32_e32 v1, 63, v0
	v_add_u32_e32 v19, v2, v18
	s_movk_i32 s5, 0x580
	v_add_u32_e32 v16, 0, v15
	v_cmp_gt_i32_e32 vcc, s5, v19
	v_lshrrev_b32_e32 v4, 5, v1
	v_and_b32_e32 v5, 31, v0
	v_lshrrev_b32_e32 v14, 3, v1
	v_lshlrev_b32_e32 v17, 3, v1
	s_and_saveexec_b64 s[22:23], vcc
	s_cbranch_execz .LBB0_1587
	s_load_dwordx4 s[12:15], s[18:19], 0xe0
	v_and_b32_e32 v0, 56, v17
	v_mul_u32_u24_e32 v2, 0x84, v0
	v_lshlrev_b32_e32 v0, 1, v0
	v_mov_b32_e32 v1, 0
	s_waitcnt lgkmcnt(0)
	v_lshl_add_u64 v[0:1], s[20:21], 0, v[0:1]
	s_mov_b64 s[10:11], 0x1100000
	s_movk_i32 s5, 0x84
	s_cmp_lg_u64 s[12:13], 0
	v_lshl_add_u64 v[6:7], v[0:1], 0, s[10:11]
	v_lshlrev_b32_e32 v0, 2, v14
	s_cselect_b64 s[8:9], -1, 0
	v_add3_u32 v20, v16, v2, v0
	v_mad_u32_u24 v0, v4, s5, v15
	v_lshlrev_b32_e32 v1, 2, v5
	v_add3_u32 v24, v0, v1, 0
	s_add_u32 s26, s12, 56
	v_cndmask_b32_e64 v0, 0, 1, s[8:9]
	s_mov_b64 s[24:25], 0
	v_or_b32_e32 v21, 8, v14
	v_or_b32_e32 v22, 16, v14
	v_or_b32_e32 v23, 24, v14
	s_addc_u32 s27, s13, 0
	s_mov_b32 s5, 0x2e8ba2e9
	s_movk_i32 s30, 0x58
	s_movk_i32 s31, 0xb00
	s_movk_i32 s34, 0x2c00
	v_cmp_ne_u32_e64 s[8:9], 1, v0
	s_movk_i32 s35, 0x400
	s_movk_i32 s36, 0x67
	s_movk_i32 s37, 0x6f
	s_movk_i32 s38, 0x77
	s_movk_i32 s39, 0x7f
	s_movk_i32 s40, 0x57f
	s_branch .LBB0_1529

.LBB0_1767:
	s_or_b64 exec, exec, s[8:9]
	s_branch .LBB0_1768
.Lp3_pass2_done:
	s_waitcnt vmcnt(0)
	s_barrier
	v_cmp_eq_u32_e32 vcc, 0, v174
	s_and_saveexec_b64 s[4:5], vcc
	s_cbranch_execz .Lp3_sig_done
	buffer_wbl2 sc1
	s_waitcnt vmcnt(0)
	v_mov_b32_e32 v0, 0xe4000
	v_mov_b32_e32 v1, 1
	global_atomic_add v0, v1, s[66:67]
	s_waitcnt vmcnt(0)
.Lp3_sig_done:
	s_or_b64 exec, exec, s[4:5]
	s_mov_b32 s99, 4
	s_branch .Lp4_entry
.LBB0_1768:
	s_cmp_eq_u32 s99, 1
	s_cbranch_scc0 .Lp0b_cont
	s_mov_b32 s99, 2
	s_branch .Lp0b_ret

.LBB0_1820:
	s_or_b64 exec, exec, s[8:9]
	s_cmp_eq_u32 s99, 2
	s_cbranch_scc0 .Lp4_entry
	s_cmp_lt_u32 s2, 16
	s_cbranch_scc0 .Lp4_entry
	s_mov_b32 s99, 3
	s_mov_b32 s96, s2
	s_lshl_b32 s2, s2, 3
	s_add_u32 s2, s2, 0x107
	s_movk_i32 s98, 0x200
	s_branch .Lp3_entry
.Lp4_entry:
	s_add_u32 s100, s2, 0x1e0
	s_sub_u32 s101, s2, 16
	s_cmp_lt_u32 s2, 16
	s_cselect_b32 s100, s100, s101
	s_cselect_b32 s101, 2, 0
	s_mov_b64 s[8:9], s[0:1]
	v_mov_b32_e32 v8, v174
	s_waitcnt lgkmcnt(0)
	s_barrier
	s_cmpk_gt_i32 s100, 0x5d7
	v_readfirstlane_b32 s22, v8
	s_cbranch_scc1 .LBB0_1836
	v_lshlrev_b32_e32 v0, 4, v8
	v_add_u32_e32 v1, 0x2000, v0
	v_ashrrev_i32_e32 v2, 31, v1
	v_lshrrev_b32_e32 v2, 22, v2
	v_add_u32_e32 v2, v1, v2
	v_ashrrev_i32_e32 v9, 10, v2
	v_mul_i32_i24_e32 v2, 0x400, v9
	v_sub_u32_e32 v1, v1, v2
	v_lshrrev_b32_e32 v2, 4, v1
	v_bitop3_b32 v1, v2, v1, 32 bitop3:0x6c
	v_ashrrev_i32_e32 v2, 31, v1
	v_lshrrev_b32_e32 v2, 26, v2
	v_add_u32_e32 v2, v1, v2
	v_lshlrev_b32_e32 v3, 3, v9
	v_ashrrev_i32_e32 v10, 6, v2
	v_and_b32_e32 v3, -16, v3
	v_add_u32_e32 v3, v10, v3
	s_load_dwordx2 s[12:13], s[8:9], 0x128
	v_and_b32_e32 v4, 3, v10
	s_mov_b32 s8, 0x1fffe0
	v_lshrrev_b32_e32 v5, 2, v3
	v_lshlrev_b32_e32 v6, 1, v3
	v_and_b32_e32 v2, 0xc0, v2
	v_and_or_b32 v4, v3, s8, v4
	v_and_b32_e32 v5, 4, v5
	v_and_b32_e32 v6, 24, v6
	v_sub_u32_e32 v1, v1, v2
	v_mov_b32_e32 v2, 1
	v_or3_b32 v4, v4, v5, v6
	v_lshlrev_b32_e32 v5, 5, v9
	v_ashrrev_i16_sdwa v1, v2, sext(v1) dst_sel:DWORD dst_unused:UNUSED_PAD src0_sel:DWORD src1_sel:BYTE_0
	v_and_b32_e32 v5, 32, v5
	v_bfe_i32 v11, v1, 0, 16
	v_add_lshl_u32 v1, v5, v11, 1
	v_lshl_add_u32 v128, v4, 11, v1
	v_lshl_add_u32 v130, v3, 11, v1
	v_bfe_i32 v1, v8, 27, 1
	v_lshrrev_b32_e32 v1, 22, v1
	v_add_u32_e32 v1, v0, v1
	v_and_b32_e32 v1, 0xfffffc00, v1
	v_sub_u32_e32 v0, v0, v1
	v_lshrrev_b32_e32 v1, 4, v0
	v_ashrrev_i32_e32 v3, 31, v8
	v_bitop3_b32 v0, v1, v0, 32 bitop3:0x6c
	v_lshrrev_b32_e32 v3, 26, v3
	v_ashrrev_i32_e32 v1, 31, v0
	v_add_u32_e32 v3, v8, v3
	s_waitcnt lgkmcnt(0)
	s_add_u32 s4, s12, 0x6c00000
	v_lshrrev_b32_e32 v1, 26, v1
	v_ashrrev_i32_e32 v13, 6, v3
	s_addc_u32 s5, s13, 0
	v_add_u32_e32 v1, v0, v1
	v_lshlrev_b32_e32 v3, 3, v13
	s_add_u32 s40, s12, 0x1100000
	v_ashrrev_i32_e32 v12, 6, v1
	v_and_b32_e32 v3, -16, v3
	s_addc_u32 s41, s13, 0
	v_add_u32_e32 v3, v12, v3
	v_and_b32_e32 v4, 3, v12
	s_ashr_i32 s43, s100, 31
	v_and_or_b32 v4, v3, s8, v4
	s_lshr_b32 s8, s43, 29
	s_add_i32 s8, s100, s8
	s_ashr_i32 s20, s22, 6
	s_ashr_i32 s10, s8, 3
	s_and_b32 s8, s8, -8
	s_ashr_i32 s9, s22, 8
	s_lshl_b32 s42, s20, 10
	s_sub_i32 s8, s100, s8
	s_cmp_lt_i32 s8, 0
	s_movk_i32 s44, 0xbc
	s_cselect_b32 s11, s44, 0xbb
	s_mul_i32 s8, s8, s11
	s_add_i32 s8, s8, s10
	s_mul_hi_i32 s10, s8, 0x2e8ba2e9
	s_lshr_b32 s11, s10, 31
	s_ashr_i32 s10, s10, 5
	v_lshrrev_b32_e32 v5, 2, v3
	v_lshlrev_b32_e32 v6, 1, v3
	v_and_b32_e32 v1, 0xc0, v1
	s_add_i32 s10, s10, s11
	v_and_b32_e32 v5, 4, v5
	v_and_b32_e32 v6, 24, v6
	v_sub_u32_e32 v0, v0, v1
	s_lshl_b32 s14, s10, 3
	v_or3_b32 v4, v4, v5, v6
	v_lshlrev_b32_e32 v5, 5, v13
	v_ashrrev_i16_sdwa v0, v2, sext(v0) dst_sel:DWORD dst_unused:UNUSED_PAD src0_sel:DWORD src1_sel:BYTE_0
	s_sub_i32 s11, 0x44, s14
	s_mulk_i32 s10, 0xb0
	v_and_b32_e32 v5, 32, v5
	v_bfe_i32 v14, v0, 0, 16
	s_min_u32 s15, s11, 8
	s_sub_i32 s18, s8, s10
	v_add_lshl_u32 v0, v5, v14, 1
	s_sext_i32_i16 s8, s18
	v_cvt_f32_ubyte0_e32 v2, s15
	v_lshl_add_u32 v132, v4, 11, v0
	v_cvt_f32_i32_e32 v1, s8
	v_rcp_iflag_f32_e32 v4, v2
	v_lshl_add_u32 v134, v3, 11, v0
	s_ashr_i32 s8, s8, 30
	s_or_b32 s8, s8, 1
	v_mul_f32_e32 v0, v1, v4
	v_trunc_f32_e32 v0, v0
	v_fma_f32 v1, -v0, v2, v1
	v_cvt_i32_f32_e32 v0, v0
	v_cmp_ge_f32_e64 s[10:11], |v1|, v2
	s_and_b64 s[10:11], s[10:11], exec
	s_cselect_b32 s8, s8, 0
	v_readfirstlane_b32 s10, v0
	s_add_i32 s8, s10, s8
	s_mul_i32 s10, s8, s15
	s_sub_i32 s10, s18, s10
	s_sext_i32_i16 s10, s10
	s_add_i32 s10, s14, s10
	s_ashr_i32 s11, s10, 31
	s_bfe_i64 s[18:19], s[8:9], 0x100000
	s_lshl_b64 s[14:15], s[10:11], 19
	s_lshl_b64 s[18:19], s[18:19], 19
	s_add_u32 s36, s40, s18
	s_addc_u32 s37, s41, s19
	s_add_i32 s45, s42, 0
	s_add_i32 m0, s45, 0x10000
	v_mov_b32_e32 v133, 0
	global_load_lds_dwordx4 v132, s[36:37]
	s_add_i32 m0, s45, 0x12000
	s_add_u32 s18, s36, 0x40000
	global_load_lds_dwordx4 v128, s[36:37]
	s_addc_u32 s19, s37, 0
	s_add_i32 m0, s45, 0x14000
	v_mov_b32_e32 v129, v133
	global_load_lds_dwordx4 v132, s[18:19]
	s_add_i32 m0, s45, 0x16000
	s_add_u32 s34, s4, s14
	s_addc_u32 s35, s5, s15
	s_add_i32 s46, s45, 0x2000
	global_load_lds_dwordx4 v128, s[18:19]
	s_mov_b32 m0, s45
	s_add_u32 s14, s34, 0x40000
	global_load_lds_dwordx4 v134, s[34:35]
	s_mov_b32 m0, s46
	s_addc_u32 s15, s35, 0
	s_add_i32 s47, s45, 0x4000
	global_load_lds_dwordx4 v130, s[34:35]
	s_mov_b32 m0, s47
	s_add_i32 s48, s45, 0x6000
	global_load_lds_dwordx4 v134, s[14:15]
	s_mov_b32 m0, s48
	v_mov_b32_e32 v135, v133
	global_load_lds_dwordx4 v130, s[14:15]
	v_mov_b32_e32 v131, v133
	s_cmp_eq_u32 s9, 1
	s_mov_b32 s49, s101
	s_mov_b32 s101, 0
	v_lshl_add_u64 v[6:7], s[36:37], 0, v[132:133]
	v_lshl_add_u64 v[4:5], s[36:37], 0, v[128:129]
	v_lshl_add_u64 v[0:1], s[34:35], 0, v[134:135]
	s_cselect_b64 s[14:15], -1, 0
	s_cmp_lg_u32 s9, 1
	v_lshl_add_u64 v[2:3], s[34:35], 0, v[130:131]
	s_cbranch_scc1 .LBB0_1823
	s_barrier

.LBB0_1826:
	s_add_i32 s49, s49, 1
	s_lshl_b32 s8, s49, 8
	s_add_u32 s28, s8, s2
	s_sub_u32 s28, s28, 32
	s_mul_i32 s8, s49, 0xf0
	s_add_u32 s8, s8, s2
	s_sub_u32 s8, s8, 16
	s_cmp_lt_u32 s49, 2
	s_cselect_b32 s28, s8, s28
	s_mov_b32 s29, 0
	v_cmp_gt_i64_e32 vcc, s[28:29], v[142:143]
	v_cmp_lt_i64_e64 s[8:9], s[28:29], v[140:141]
	s_cbranch_vccnz .LBB0_1828
	s_ashr_i32 s24, s28, 31
	s_lshr_b32 s24, s24, 29
	s_add_i32 s24, s28, s24
	s_ashr_i32 s25, s24, 3
	s_and_b32 s24, s24, -8
	s_sub_i32 s24, s28, s24
	s_cmp_lt_i32 s24, 0
	s_cselect_b32 s26, s44, 0xbb
	s_mul_i32 s24, s24, s26
	s_add_i32 s24, s24, s25
	s_mul_hi_i32 s25, s24, 0x2e8ba2e9
	s_lshr_b32 s26, s25, 31
	s_ashr_i32 s25, s25, 5
	s_add_i32 s25, s25, s26
	s_lshl_b32 s26, s25, 3
	s_sub_i32 s27, 0x44, s26
	s_min_i32 s27, s27, 8
	s_abs_i32 s28, s27
	v_cvt_f32_u32_e32 v0, s28
	s_sub_i32 s30, 0, s28
	s_mulk_i32 s25, 0xb0
	s_sub_i32 s25, s24, s25
	v_rcp_iflag_f32_e32 v0, v0
	s_abs_i32 s24, s25
	s_xor_b32 s29, s25, s27
	s_ashr_i32 s29, s29, 31
	v_mul_f32_e32 v0, 0x4f7ffffe, v0
	v_cvt_u32_f32_e32 v0, v0
	s_nop 0
	v_readfirstlane_b32 s31, v0
	s_mul_i32 s30, s30, s31
	s_mul_hi_u32 s30, s31, s30
	s_add_i32 s31, s31, s30
	s_mul_hi_u32 s30, s24, s31
	s_mul_i32 s31, s30, s28
	s_sub_i32 s24, s24, s31
	s_add_i32 s38, s30, 1
	s_sub_i32 s31, s24, s28
	s_cmp_ge_u32 s24, s28
	s_cselect_b32 s30, s38, s30
	s_cselect_b32 s24, s31, s24
	s_add_i32 s31, s30, 1
	s_cmp_ge_u32 s24, s28
	s_cselect_b32 s24, s31, s30
	s_xor_b32 s24, s24, s29
	s_sub_i32 s24, s24, s29
	s_mul_i32 s27, s24, s27
	s_sub_i32 s25, s25, s27
	s_add_i32 s26, s26, s25
.LBB0_1828:
	s_cmp_lt_i32 s26, 64
	s_cbranch_scc1 .Lp4_nowait
	s_and_b64 vcc, exec, s[8:9]
	s_cbranch_vccz .Lp4_nowait
	s_cmp_eq_u32 s101, 1
	s_cbranch_scc1 .Lp4_nowait
	v_mov_b32_e32 v244, 0xe4000
	s_mov_b32 s96, 0
.Lp4_spin:
	global_load_dword v245, v244, s[66:67] sc1
	s_waitcnt vmcnt(0)
	v_readfirstlane_b32 s97, v245
	s_nop 3
	s_cmp_ge_u32 s97, 16
	s_cbranch_scc1 .Lp4_acq
	s_sleep 8
	s_add_u32 s96, s96, 1
	s_cmp_lt_u32 s96, 0x4000
	s_cbranch_scc1 .Lp4_spin
.Lp4_acq:
	buffer_inv sc1
	s_waitcnt vmcnt(0)
	s_mov_b32 s101, 1
